# attention main loop: K/V staging ds_writes moved into the P.V MFMA shadow with counted lgkmcnt (plus v10 epilogues)
# speedup vs baseline: 1.0125x; 1.0068x over previous
; template <int DQK, bool MLA> ...
;     ...
;     auto substep = [&](f32x16& a, f32x16& b, int knext_ofs, int vofs, int h, int kafter_ofs) __attribute__((always_inline)) {
;         const LAS unsigned char* kb = lds + knext_ofs + r32 * KPITCH + hi * 16;
;         const LAS unsigned char* vb = lds + vofs + r32 * 144 + hi * 16 + h * 64;
;         u32x4 pw0, pw1; bf16x8 vf0[4], vf1[4], kr[3];
;         kr[0] = kp0; kr[1] = kp1;
;         float rs0 = rs_early;
;         __builtin_amdgcn_sched_barrier(0);
; #pragma unroll
;         for (int d0 = 0; d0 < KS; ++d0) {
;             if (d0 + 2 < KS) kr[(d0 + 2) % 3] = *(const LAS bf16x8*)(kb + (d0 + 2) * 32);
;             if (d0 == KS - 3) {
; #pragma unroll
;                 for (int d = 0; d < 4; ++d) vf0[d] = *(const LAS bf16x8*)(vb + d * 4608);
;             }
;             if (d0 == 0) { const f32x16 z16 = {0.f, 0.f, 0.f, 0.f, 0.f, 0.f, 0.f, 0.f, 0.f, 0.f, 0.f, 0.f, 0.f, 0.f, 0.f, 0.f};
;                 b = __builtin_amdgcn_mfma_f32_32x32x16_bf16(kr[0], qf[0], z16, 0, 0, 0); }
;             else b = __builtin_amdgcn_mfma_f32_32x32x16_bf16(kr[d0 % 3], qf[d0], b, 0, 0, 0);
; #pragma unroll
;             for (int e = 6 + (10 * d0) / KS; e < 6 + (10 * (d0 + 1)) / KS; ++e) {
;                 const float x = __builtin_amdgcn_exp2f(a[e]);
;                 a[e] = x;
;                 rs0 += x;
;                 if (e == 7)  { pw0.x = pk(a[0], a[1]); pw0.y = pk(a[2], a[3]);   pw0.z = pk(a[4], a[5]);   pw0.w = pk(a[6], a[7]); }
;                 if (e == 15) { pw1.x = pk(a[8], a[9]); pw1.y = pk(a[10], a[11]); pw1.z = pk(a[12], a[13]); pw1.w = pk(a[14], a[15]); }
;             }
;             __builtin_amdgcn_sched_barrier(0);
;         }
;         l_run += rs0;
;         float rs_n = 0.f;
; #pragma unroll
;         for (int kk = 0; kk < 2; ++kk) {
;             if (kk == 0) {
; #pragma unroll
;                 for (int d = 0; d < 4; ++d) vf1[d] = *(const LAS bf16x8*)(vb + d * 4608 + 32);
;             } else { const LAS unsigned char* ka = lds + kafter_ofs + r32 * KPITCH + hi * 16; kp0 = *(const LAS bf16x8*)(ka); kp1 = *(const LAS bf16x8*)(ka + 32); }
;             const bf16x8 pb = __builtin_bit_cast(bf16x8, kk ? pw1 : pw0);
; #pragma unroll
;             for (int d = 0; d < 4; ++d) {
;                 o[d] = __builtin_amdgcn_mfma_f32_32x32x16_bf16(kk ? vf1[d] : vf0[d], pb, o[d], 0, 0, 0);
.LBB0_1043:
	s_or_b64 exec, exec, s[34:35]
	s_cmp_gt_u32 s68, s48
	s_cbranch_scc1 .LBB0_1045
	s_bitcmp1_b32 s68, 0
	s_cselect_b32 s34, s87, 0x12c00
	v_add_u32_e32 v193, s70, v183
	v_add_u32_e32 v208, s34, v175
	s_waitcnt lgkmcnt(1)
	v_mfma_f32_32x32x16_bf16 v[80:95], v[80:83], v[100:103], 0
	ds_read_b128 v[210:213], v193 offset:12864
	s_waitcnt lgkmcnt(1)
	v_mfma_f32_32x32x16_bf16 v[80:95], v[160:163], v[104:107], v[80:95]
	v_exp_f32_e32 v70, v70
	ds_read_b128 v[214:217], v193 offset:12896
	v_add_f32_e32 v186, v70, v186
	s_waitcnt lgkmcnt(1)
	v_mfma_f32_32x32x16_bf16 v[80:95], v[210:213], v[108:111], v[80:95]
	ds_read_b128 v[160:163], v193 offset:12928
	v_exp_f32_e32 v71, v71
	s_nop 0
	v_cvt_pk_bf16_f32 v64, v64, v65
	s_nop 0
	v_cvt_pk_bf16_f32 v65, v66, v67
	s_nop 0
	v_cvt_pk_bf16_f32 v66, v68, v69
	s_nop 0
	v_cvt_pk_bf16_f32 v67, v70, v71
	s_nop 0
	v_add_f32_e32 v186, v71, v186
	s_waitcnt lgkmcnt(1)
	v_mfma_f32_32x32x16_bf16 v[80:95], v[214:217], v[112:115], v[80:95]
	ds_read_b128 v[68:71], v193 offset:12960
	v_exp_f32_e32 v194, v72
	s_nop 0
	v_add_f32_e32 v72, v194, v186
	s_waitcnt lgkmcnt(1)
	v_mfma_f32_32x32x16_bf16 v[80:95], v[160:163], v[116:119], v[80:95]
	v_exp_f32_e32 v186, v73
	ds_read_b128 v[210:213], v193 offset:12992
	v_add_f32_e32 v72, v186, v72
	s_waitcnt lgkmcnt(1)
	v_mfma_f32_32x32x16_bf16 v[80:95], v[68:71], v[120:123], v[80:95]
	ds_read_b128 v[160:163], v193 offset:13024
	v_exp_f32_e32 v195, v74
	s_nop 0
	v_add_f32_e32 v72, v195, v72
	s_waitcnt lgkmcnt(1)
	v_mfma_f32_32x32x16_bf16 v[80:95], v[210:213], v[124:127], v[80:95]
	ds_read_b128 v[68:71], v193 offset:13056
	s_waitcnt lgkmcnt(1)
	v_mfma_f32_32x32x16_bf16 v[80:95], v[160:163], v[128:131], v[80:95]
	v_exp_f32_e32 v196, v75
	ds_read_b128 v[210:213], v193 offset:13088
	v_add_f32_e32 v160, v196, v72
	s_waitcnt lgkmcnt(1)
	v_mfma_f32_32x32x16_bf16 v[80:95], v[68:71], v[136:139], v[80:95]
	ds_read_b128 v[72:75], v193 offset:13120
	v_exp_f32_e32 v76, v76
	s_nop 0
	v_add_f32_e32 v197, v76, v160
	ds_read_b128 v[68:71], v193 offset:13152
	ds_read_b128 v[160:163], v208
	ds_read_b128 v[214:217], v208 offset:4608
	ds_read_b128 v[218:221], v208 offset:9216
	ds_read_b128 v[222:225], v208 offset:13824
	s_waitcnt lgkmcnt(6)
	v_mfma_f32_32x32x16_bf16 v[80:95], v[210:213], v[144:147], v[80:95]
	v_exp_f32_e32 v77, v77
	s_nop 0
	v_add_f32_e32 v193, v77, v197
	s_waitcnt lgkmcnt(5)
	v_mfma_f32_32x32x16_bf16 v[80:95], v[72:75], v[132:135], v[80:95]
	v_exp_f32_e32 v72, v78
	s_nop 0
	v_add_f32_e32 v73, v72, v193
	s_waitcnt lgkmcnt(4)
	v_mfma_f32_32x32x16_bf16 v[80:95], v[68:71], v[140:143], v[80:95]
	v_exp_f32_e32 v71, v79
	s_nop 0
	v_cvt_pk_bf16_f32 v68, v194, v186
	s_nop 0
	v_cvt_pk_bf16_f32 v69, v195, v196
	s_nop 0
	v_cvt_pk_bf16_f32 v70, v76, v77
	s_nop 0
	v_add_f32_e32 v73, v71, v73
	s_nop 0
	v_cvt_pk_bf16_f32 v71, v72, v71
	s_waitcnt lgkmcnt(3)
	v_mfma_f32_32x32x16_bf16 v[48:63], v[160:163], v[64:67], v[48:63]
	v_add_f32_e32 v187, v187, v73
	ds_read_b128 v[72:75], v208 offset:32
	ds_read_b128 v[76:79], v208 offset:4640
	ds_read_b128 v[160:163], v208 offset:9248
	ds_read_b128 v[210:213], v208 offset:13856
	s_nop 1
	v_exp_f32_e32 v186, v80
	v_exp_f32_e32 v193, v81
	s_waitcnt lgkmcnt(6)
	v_mfma_f32_32x32x16_bf16 v[32:47], v[214:217], v[64:67], v[32:47]
	s_waitcnt lgkmcnt(5)
	v_mfma_f32_32x32x16_bf16 v[16:31], v[218:221], v[64:67], v[16:31]
	s_waitcnt lgkmcnt(4)
	v_mfma_f32_32x32x16_bf16 v[0:15], v[222:225], v[64:67], v[0:15]
	s_waitcnt lgkmcnt(3)
	v_mfma_f32_32x32x16_bf16 v[48:63], v[72:75], v[68:71], v[48:63]
	v_exp_f32_e32 v195, v82
	v_add_u32_e32 v194, s72, v183
	v_exp_f32_e32 v196, v83
	ds_read_b128 v[64:67], v194
	ds_read_b128 v[214:217], v194 offset:32
	v_exp_f32_e32 v84, v84
	v_add_f32_e32 v72, 0, v186
	v_exp_f32_e32 v85, v85
	s_waitcnt lgkmcnt(4)
	v_mfma_f32_32x32x16_bf16 v[32:47], v[76:79], v[68:71], v[32:47]
	v_add_f32_e32 v72, v193, v72
	v_add_f32_e32 v72, v195, v72
	v_add_f32_e32 v72, v196, v72
	v_add_f32_e32 v72, v84, v72
	v_add_f32_e32 v197, v85, v72
	s_waitcnt lgkmcnt(3)
	v_mfma_f32_32x32x16_bf16 v[16:31], v[160:163], v[68:71], v[16:31]
	s_waitcnt lgkmcnt(2)
	v_mfma_f32_32x32x16_bf16 v[0:15], v[210:213], v[68:71], v[0:15]
	s_waitcnt lgkmcnt(1)
	v_mfma_f32_32x32x16_bf16 v[64:79], v[64:67], v[100:103], 0
	ds_read_b128 v[80:83], v194 offset:64
	s_waitcnt lgkmcnt(1)
	v_mfma_f32_32x32x16_bf16 v[64:79], v[214:217], v[104:107], v[64:79]
	ds_read_b128 v[160:163], v194 offset:96
	v_exp_f32_e32 v86, v86
	s_nop 0
	v_add_f32_e32 v197, v86, v197
	s_waitcnt lgkmcnt(1)
; #define LAS __attribute__((address_space(3)))
; template <int DQK, bool MLA> ...
;     ...
;         for (int kk = 0; kk < 2; ++kk) {
;             if (kk == 0) {
; #pragma unroll
;                 for (int d = 0; d < 4; ++d) vf1[d] = *(const LAS bf16x8*)(vb + d * 4608 + 32);
;             } else { const LAS unsigned char* ka = lds + kafter_ofs + r32 * KPITCH + hi * 16; kp0 = *(const LAS bf16x8*)(ka); kp1 = *(const LAS bf16x8*)(ka + 32); }
;             const bf16x8 pb = __builtin_bit_cast(bf16x8, kk ? pw1 : pw0);
; #pragma unroll
;             for (int d = 0; d < 4; ++d) {
;                 o[d] = __builtin_amdgcn_mfma_f32_32x32x16_bf16(kk ? vf1[d] : vf0[d], pb, o[d], 0, 0, 0);
;                 const int e = 4 * kk + d - 2;
;                 if (e >= 0) { const float x = __builtin_amdgcn_exp2f(b[e]); b[e] = x; rs_n += x; }
;             }
;             __builtin_amdgcn_sched_barrier(0);
;         }
;         rs_early = rs_n;
;     };
;     int kc = 0, kn = KT_BYTES, kn2 = 2 * KT_BYTES;
;     for (int t = 0; t < NT; ++t) {
;         const bool has_k2 = (t + 2 < NT), has_v1 = (t + 1 < NT), active = (t <= tmax_w);
;         const int vofs = 3 * KT_BYTES + (t & 1) * VT_BYTES;
;         if (has_k2) gload_k(t + 2);
;         if (has_v1) gload_v(t + 1);
;         if (active) substep(sX, sY, kc + 32 * KPITCH, vofs, 0, kn);
;         if (active) substep(sY, sX, kn, vofs, 1, kn + 32 * KPITCH);
;         if (has_k2) sts_k(kn2);
;         if (has_v1) sts_v((t + 1) & 1);
	v_mfma_f32_32x32x16_bf16 v[64:79], v[80:83], v[108:111], v[64:79]
	ds_read_b128 v[210:213], v194 offset:128
	v_exp_f32_e32 v83, v87
	s_nop 0
	v_cvt_pk_bf16_f32 v80, v186, v193
	s_nop 0
	v_cvt_pk_bf16_f32 v81, v195, v196
	s_nop 0
	v_cvt_pk_bf16_f32 v82, v84, v85
	s_nop 0
	v_add_f32_e32 v197, v83, v197
	s_nop 0
	v_cvt_pk_bf16_f32 v83, v86, v83
	s_waitcnt lgkmcnt(1)
	v_mfma_f32_32x32x16_bf16 v[64:79], v[160:163], v[112:115], v[64:79]
	ds_read_b128 v[84:87], v194 offset:160
	v_exp_f32_e32 v186, v88
	s_nop 0
	v_add_f32_e32 v88, v186, v197
	s_waitcnt lgkmcnt(1)
	v_mfma_f32_32x32x16_bf16 v[64:79], v[210:213], v[116:119], v[64:79]
	ds_read_b128 v[160:163], v194 offset:192
	v_exp_f32_e32 v196, v89
	s_nop 0
	v_add_f32_e32 v88, v196, v88
	s_waitcnt lgkmcnt(1)
	v_mfma_f32_32x32x16_bf16 v[64:79], v[84:87], v[120:123], v[64:79]
	ds_read_b128 v[210:213], v194 offset:224
	v_exp_f32_e32 v226, v90
	s_nop 0
	v_add_f32_e32 v193, v226, v88
	s_waitcnt lgkmcnt(1)
	v_mfma_f32_32x32x16_bf16 v[64:79], v[160:163], v[124:127], v[64:79]
	ds_read_b128 v[84:87], v194 offset:256
	s_waitcnt lgkmcnt(1)
	v_mfma_f32_32x32x16_bf16 v[64:79], v[210:213], v[128:131], v[64:79]
	ds_read_b128 v[160:163], v194 offset:288
	v_exp_f32_e32 v195, v91
	s_waitcnt lgkmcnt(1)
	v_mfma_f32_32x32x16_bf16 v[64:79], v[84:87], v[136:139], v[64:79]
	ds_read_b128 v[88:91], v194 offset:320
	v_exp_f32_e32 v197, v92
	ds_read_b128 v[84:87], v194 offset:352
	ds_read_b128 v[210:213], v208 offset:64
	ds_read_b128 v[214:217], v208 offset:4672
	ds_read_b128 v[218:221], v208 offset:9280
	ds_read_b128 v[222:225], v208 offset:13888
	s_waitcnt lgkmcnt(6)
	v_mfma_f32_32x32x16_bf16 v[64:79], v[160:163], v[144:147], v[64:79]
	v_exp_f32_e32 v209, v93
	s_waitcnt lgkmcnt(5)
	v_mfma_f32_32x32x16_bf16 v[64:79], v[88:91], v[132:135], v[64:79]
	v_exp_f32_e32 v227, v94
	s_waitcnt lgkmcnt(4)
	v_mfma_f32_32x32x16_bf16 v[64:79], v[84:87], v[140:143], v[64:79]
	v_exp_f32_e32 v229, v95
	s_nop 0
	v_cvt_pk_bf16_f32 v84, v186, v196
	s_nop 0
	v_cvt_pk_bf16_f32 v85, v226, v195
	s_nop 0
	v_cvt_pk_bf16_f32 v86, v197, v209
	s_nop 0
	v_cvt_pk_bf16_f32 v87, v227, v229
	s_waitcnt lgkmcnt(3)
	v_mfma_f32_32x32x16_bf16 v[48:63], v[210:213], v[80:83], v[48:63]
	s_add_i32 s98, s68, 1
	s_bitcmp1_b32 s98, 0
	s_cselect_b32 s98, 0x4800, 0
	v_add_u32_e32 v230, s71, v172
	v_add_u32_e32 v231, s71, v174
	v_add_u32_e32 v232, s71, v184
	v_add_u32_e32 v233, s98, v173
	s_waitcnt vmcnt(4)
	ds_write_b128 v230, v[148:151]
	v_exp_f32_e32 v64, v64
	v_exp_f32_e32 v65, v65
	s_waitcnt lgkmcnt(3)
	v_mfma_f32_32x32x16_bf16 v[32:47], v[214:217], v[80:83], v[32:47]
	ds_read_b128 v[88:91], v208 offset:96
	ds_read_b128 v[92:95], v208 offset:4704
	ds_read_b128 v[210:213], v208 offset:9312
	ds_read_b128 v[214:217], v208 offset:13920
	s_waitcnt lgkmcnt(6)
	v_mfma_f32_32x32x16_bf16 v[16:31], v[218:221], v[80:83], v[16:31]
	s_waitcnt vmcnt(3)
	ds_write_b128 v231, v[152:155]
	s_waitcnt lgkmcnt(6)
	v_mfma_f32_32x32x16_bf16 v[0:15], v[222:225], v[80:83], v[0:15]
	v_exp_f32_e32 v66, v66
	s_waitcnt vmcnt(2)
	ds_write_b128 v232, v[156:159] offset:256
	s_waitcnt lgkmcnt(5)
	v_mfma_f32_32x32x16_bf16 v[48:63], v[88:91], v[84:87], v[48:63]
	v_exp_f32_e32 v67, v67
	ds_read_b128 v[80:83], v194 offset:12800
	ds_read_b128 v[160:163], v194 offset:12832
	v_exp_f32_e32 v68, v68
	v_mov_b32_e32 v194, v64
	v_exp_f32_e32 v69, v69
	v_pk_add_f32 v[88:89], v[194:195], v[192:193]
	v_mov_b32_e32 v196, v65
	s_waitcnt lgkmcnt(6)
	v_mfma_f32_32x32x16_bf16 v[32:47], v[92:95], v[84:87], v[32:47]
	v_add_f32_e64 v88, v196, v88
	v_add_f32_e64 v89, v197, v89
	v_mov_b32_e32 v208, v66
	v_add_f32_e64 v88, v208, v88
	v_add_f32_e64 v89, v209, v89
	v_mov_b32_e32 v226, v67
	v_pk_add_f32 v[88:89], v[226:227], v[88:89]
	v_mov_b32_e32 v228, v68
	v_pk_add_f32 v[88:89], v[228:229], v[88:89]
	s_waitcnt vmcnt(1)
	ds_write_b128 v233, v[164:167]
	s_waitcnt lgkmcnt(6)
	v_mfma_f32_32x32x16_bf16 v[16:31], v[210:213], v[84:87], v[16:31]
	v_mov_b32_e32 v186, v69
	v_add_f32_e64 v186, v186, v88
	v_add_f32_e64 v187, v187, v89
	s_waitcnt vmcnt(0)
	ds_write_b128 v233, v[168:171] offset:8192
	s_waitcnt lgkmcnt(6)
	v_mfma_f32_32x32x16_bf16 v[0:15], v[214:217], v[84:87], v[0:15]
	s_add_i32 s68, s68, 1
	s_add_i32 s73, s71, 0
	s_bitcmp1_b32 s68, 0
	s_cselect_b64 s[34:35], -1, 0
	s_and_b64 s[66:67], s[34:35], exec
	s_cselect_b32 s66, 0x4800, 0
	s_and_saveexec_b64 s[66:67], s[4:5]
	ds_write_b128 v233, v[96:99] offset:16384
	s_or_b64 exec, exec, s[66:67]
	s_branch .Lattn_wtail

; template <int DQK, bool MLA> ...
;     ...
;     for (int t = 0; t < NT; ++t) {
;         const bool has_k2 = (t + 2 < NT), has_v1 = (t + 1 < NT), active = (t <= tmax_w);
;         const int vofs = 3 * KT_BYTES + (t & 1) * VT_BYTES;
;         if (has_k2) gload_k(t + 2);
;         if (has_v1) gload_v(t + 1);
;         if (active) substep(sX, sY, kc + 32 * KPITCH, vofs, 0, kn);
;         if (active) substep(sY, sX, kn, vofs, 1, kn + 32 * KPITCH);
;         if (has_k2) sts_k(kn2);
;         if (has_v1) sts_v((t + 1) & 1);
;         __syncthreads();
;         const int tmp = kc; kc = kn; kn = kn2; kn2 = tmp;
.Lattn_wtail:
	v_lshl_add_u64 v[190:191], v[190:191], 0, s[20:21]
	v_lshl_add_u64 v[202:203], v[202:203], 0, s[0:1]
	v_lshl_add_u64 v[204:205], v[204:205], 0, s[14:15]
	s_cmp_eq_u32 s49, s68
	v_lshl_add_u64 v[206:207], v[206:207], 0, s[14:15]
	s_waitcnt lgkmcnt(0)
	s_barrier
	s_cbranch_scc1 .LBB0_1049
	s_mov_b32 s34, s70
	s_mov_b32 s70, s72
	s_branch .LBB0_1041

; __global__ void __launch_bounds__(NTHR, 2) hybrid_fwd(Params P) {
;     extern __shared__ __attribute__((aligned(16))) unsigned char lds_raw[];
	.amdhsa_kernel _Z10hybrid_fwd6Params
		.amdhsa_group_segment_fixed_size 0
		.amdhsa_private_segment_fixed_size 0
		.amdhsa_kernarg_size 448
		.amdhsa_user_sgpr_count 2
		.amdhsa_user_sgpr_dispatch_ptr 0
		.amdhsa_user_sgpr_queue_ptr 0
		.amdhsa_user_sgpr_kernarg_segment_ptr 1
		.amdhsa_user_sgpr_dispatch_id 0
		.amdhsa_user_sgpr_kernarg_preload_length 0
		.amdhsa_user_sgpr_kernarg_preload_offset 0
		.amdhsa_user_sgpr_private_segment_size 0
		.amdhsa_uses_dynamic_stack 0
		.amdhsa_enable_private_segment 0
		.amdhsa_system_sgpr_workgroup_id_x 1
		.amdhsa_system_sgpr_workgroup_id_y 0
		.amdhsa_system_sgpr_workgroup_id_z 0
		.amdhsa_system_sgpr_workgroup_info 0
		.amdhsa_system_vgpr_workitem_id 2
		.amdhsa_next_free_vgpr 256
		.amdhsa_next_free_sgpr 100
		.amdhsa_accum_offset 256
		.amdhsa_reserve_vcc 1
		.amdhsa_float_round_mode_32 0
		.amdhsa_float_round_mode_16_64 0
		.amdhsa_float_denorm_mode_32 3
		.amdhsa_float_denorm_mode_16_64 3
		.amdhsa_dx10_clamp 1
		.amdhsa_ieee_mode 1
		.amdhsa_fp16_overflow 0
		.amdhsa_tg_split 0
		.amdhsa_exception_fp_ieee_invalid_op 0
		.amdhsa_exception_fp_denorm_src 0
		.amdhsa_exception_fp_ieee_div_zero 0
		.amdhsa_exception_fp_ieee_overflow 0
		.amdhsa_exception_fp_ieee_underflow 0
		.amdhsa_exception_fp_ieee_inexact 0
		.amdhsa_exception_int_div_zero 0
	.end_amdhsa_kernel

; __global__ void __launch_bounds__(NTHR, 2) hybrid_fwd(Params P) {
;     extern __shared__ __attribute__((aligned(16))) unsigned char lds_raw[];
amdhsa.kernels:
  - .agpr_count:     0
    .args:
      - .offset:         0
        .size:           192
        .value_kind:     by_value
      - .offset:         192
        .size:           4
        .value_kind:     hidden_block_count_x
      - .offset:         196
        .size:           4
        .value_kind:     hidden_block_count_y
      - .offset:         200
        .size:           4
        .value_kind:     hidden_block_count_z
      - .offset:         204
        .size:           2
        .value_kind:     hidden_group_size_x
      - .offset:         206
        .size:           2
        .value_kind:     hidden_group_size_y
      - .offset:         208
        .size:           2
        .value_kind:     hidden_group_size_z
      - .offset:         210
        .size:           2
        .value_kind:     hidden_remainder_x
      - .offset:         212
        .size:           2
        .value_kind:     hidden_remainder_y
      - .offset:         214
        .size:           2
        .value_kind:     hidden_remainder_z
      - .offset:         232
        .size:           8
        .value_kind:     hidden_global_offset_x
      - .offset:         240
        .size:           8
        .value_kind:     hidden_global_offset_y
      - .offset:         248
        .size:           8
        .value_kind:     hidden_global_offset_z
      - .offset:         256
        .size:           2
        .value_kind:     hidden_grid_dims
      - .offset:         280
        .size:           8
        .value_kind:     hidden_multigrid_sync_arg
      - .offset:         312
        .size:           4
        .value_kind:     hidden_dynamic_lds_size
    .group_segment_fixed_size: 0
    .kernarg_segment_align: 8
    .kernarg_segment_size: 448
    .language:       OpenCL C
    .language_version:
      - 2
      - 0
    .max_flat_workgroup_size: 512
    .name:           _Z10hybrid_fwd6Params
    .private_segment_fixed_size: 0
    .sgpr_count:     106
    .sgpr_spill_count: 254
    .symbol:         _Z10hybrid_fwd6Params.kd
    .uniform_work_group_size: 1
    .uses_dynamic_stack: false
    .vgpr_count:     256
    .vgpr_spill_count: 0
    .wavefront_size: 64
